# 7 local seams + 6 seams as group-rendezvous (local barrier, last arriver wbl2, all wait for 8 group generations) instead of XCC two-level barrier
# baseline (speedup 1.0000x reference)
; __device__ __forceinline__ int lane_id_() { int l; asm volatile("v_mbcnt_lo_u32_b32 %0, -1, 0\n\tv_mbcnt_hi_u32_b32 %0, -1, %0" : "=v"(l)); return l; }
; __device__ __forceinline__ unsigned xb_ld(unsigned* p)              { return __hip_atomic_load(p, __ATOMIC_RELAXED, __HIP_MEMORY_SCOPE_AGENT); }
; __device__ __forceinline__ unsigned xb_add(unsigned* p, unsigned v) { return __hip_atomic_fetch_add(p, v, __ATOMIC_RELAXED, __HIP_MEMORY_SCOPE_AGENT); }
; #define XB_SPIN(cond, bar) do { unsigned _sp = 0; while (cond) { __builtin_amdgcn_s_sleep(1); \
;     if ((++_sp & 255u) == 0u) { if (xb_ld(&(bar)[XB_TMO])) break; if (_sp > XB_SPIN_CAP) { atomicAdd(&(bar)[XB_TMO], 1u); break; } } } } while (0)
; __device__ __forceinline__ void xcd_barrier(const XcdBarrier& b, int wave_s) {
;     asm volatile("s_waitcnt vmcnt(0)" ::: "memory");
;     __syncthreads();
;     if (wave_s == 0 && lane_id_() == 0) {
;         unsigned* bar = b.bar;
;         __builtin_amdgcn_s_waitcnt(0);
;         unsigned nloc = b.st[0], nx = b.st[1];
;         if (nloc == 0u) { xcd_barrier_complete(bar, b.x, nloc, nx); b.st[0] = nloc; b.st[1] = nx; }
;         const unsigned old = xb_add(&bar[XB_XSUB(b.x)], 1u);
;         const unsigned gen = old / nloc;
;         if (old + 1u == (gen + 1u) * nloc) {
;             __builtin_amdgcn_fence(__ATOMIC_RELEASE, "agent");
;             asm volatile("s_waitcnt vmcnt(0)" ::: "memory");
;             const unsigned og = xb_add(&bar[XB_TOP], 1u);
;             const unsigned tg = og / nx;
;             if (og + 1u == (tg + 1u) * nx) xb_add(&bar[XB_TOPGEN], 1u);
;             else XB_SPIN(xb_ld(&bar[XB_TOPGEN]) == tg, bar);
;             __builtin_amdgcn_fence(__ATOMIC_ACQUIRE, "agent");
;             xb_add(&bar[XB_XGEN(b.x)], 1u);
;             asm volatile("s_waitcnt vmcnt(0)" ::: "memory");
;         } else {
;             XB_SPIN(xb_ld(&bar[XB_XGEN(b.x)]) == gen, bar);
;             __builtin_amdgcn_fence(__ATOMIC_ACQUIRE, "agent");
;             asm volatile("s_waitcnt vmcnt(0)" ::: "memory");
;         }
.LBB0_252:
	s_waitcnt vmcnt(0)
	v_cndmask_b32_e64 v0, 0, 1, s[4:5]
	v_cmp_ne_u32_e64 s[2:3], 1, v0
	s_andn2_b64 vcc, exec, s[4:5]
	s_waitcnt vmcnt(0)
	s_barrier
	s_cbranch_vccnz .LBB0_306
	v_mbcnt_lo_u32_b32 v0, -1, 0
	v_mbcnt_hi_u32_b32 v0, -1, v0
	s_nop 0
	v_cmp_eq_u32_e32 vcc, 0, v0
	s_and_saveexec_b64 s[4:5], vcc
	s_cbranch_execz .LBB0_305
	s_cmp_eq_u32 s101, 1
	s_cbranch_scc0 .Lglob_S2
	s_and_b32 s98, s33, 7
	s_lshl_b32 s99, s98, 2
	s_addk_i32 s99, 0x4800
	v_mov_b32_e32 v3, s99
	s_lshl_b32 s98, s98, 8
	s_addk_i32 s98, 0x4000
	v_mov_b32_e32 v0, s98
	v_mov_b32_e32 v1, 1
	global_atomic_add v2, v0, v1, s[44:45] sc0
	s_waitcnt vmcnt(0)
	v_readfirstlane_b32 s98, v2
	s_nop 3
	s_add_u32 s99, s98, 1
	s_and_b32 s99, s99, 31
	s_lshr_b32 s98, s98, 5
	s_cmp_eq_u32 s99, 0
	s_cbranch_scc0 .Llw_S2
	buffer_wbl2 sc1
	s_waitcnt vmcnt(0)
	global_atomic_add v3, v1, s[44:45]
.Llw_S2:
	s_add_u32 s98, s98, 1
	s_mov_b64 exec, 0xff
	v_mbcnt_lo_u32_b32 v0, -1, 0
	v_lshlrev_b32_e32 v0, 2, v0
	v_add_u32_e32 v0, 0x4800, v0
	s_mov_b32 s99, 0
.Lls_S2:
	global_load_dword v2, v0, s[44:45] sc1
	s_waitcnt vmcnt(0)
	v_cmp_gt_u32_e32 vcc, s98, v2
	s_nop 3
	s_cmp_eq_u64 vcc, 0
	s_cbranch_scc1 .Lrd_S2
	s_sleep 1
	s_add_u32 s99, s99, 1
	s_cmp_lt_u32 s99, 0x4000
	s_cbranch_scc1 .Lls_S2
.Lrd_S2:
	s_mov_b64 exec, 1

; __device__ __forceinline__ int lane_id_() { int l; asm volatile("v_mbcnt_lo_u32_b32 %0, -1, 0\n\tv_mbcnt_hi_u32_b32 %0, -1, %0" : "=v"(l)); return l; }
; __device__ __forceinline__ unsigned xb_add(unsigned* p, unsigned v) { return __hip_atomic_fetch_add(p, v, __ATOMIC_RELAXED, __HIP_MEMORY_SCOPE_AGENT); }
; __device__ __forceinline__ void xcd_barrier(const XcdBarrier& b, int wave_s) {
;     asm volatile("s_waitcnt vmcnt(0)" ::: "memory");
;     __syncthreads();
;     if (wave_s == 0 && lane_id_() == 0) {
;         unsigned* bar = b.bar;
;         __builtin_amdgcn_s_waitcnt(0);
;         unsigned nloc = b.st[0], nx = b.st[1];
;         if (nloc == 0u) { xcd_barrier_complete(bar, b.x, nloc, nx); b.st[0] = nloc; b.st[1] = nx; }
;         const unsigned old = xb_add(&bar[XB_XSUB(b.x)], 1u);
;         const unsigned gen = old / nloc;
;         if (old + 1u == (gen + 1u) * nloc) {
;             __builtin_amdgcn_fence(__ATOMIC_RELEASE, "agent");
;             asm volatile("s_waitcnt vmcnt(0)" ::: "memory");
;             const unsigned og = xb_add(&bar[XB_TOP], 1u);
.LBB0_354:
	s_waitcnt vmcnt(0)
	s_and_b64 vcc, exec, s[2:3]
	s_waitcnt lgkmcnt(0)
	s_barrier
	s_cbranch_vccnz .LBB0_408
	v_mbcnt_lo_u32_b32 v0, -1, 0
	v_mbcnt_hi_u32_b32 v0, -1, v0
	s_nop 0
	v_cmp_eq_u32_e32 vcc, 0, v0
	s_and_saveexec_b64 s[6:7], vcc
	s_cbranch_execz .LBB0_407
	s_cmp_eq_u32 s101, 1
	s_cbranch_scc0 .Lglob_S3
	s_and_b32 s98, s33, 7
	s_lshl_b32 s99, s98, 2
	s_addk_i32 s99, 0x4800
	v_mov_b32_e32 v3, s99
	s_lshl_b32 s98, s98, 8
	s_addk_i32 s98, 0x4000
	v_mov_b32_e32 v0, s98
	v_mov_b32_e32 v1, 1
	global_atomic_add v2, v0, v1, s[44:45] sc0
	s_waitcnt vmcnt(0)
	v_readfirstlane_b32 s98, v2
	s_nop 3
	s_add_u32 s99, s98, 1
	s_and_b32 s99, s99, 31
	s_lshr_b32 s98, s98, 5
	s_cmp_eq_u32 s99, 0
	s_cbranch_scc0 .Llw_S3
	buffer_wbl2 sc1
	s_waitcnt vmcnt(0)
	global_atomic_add v3, v1, s[44:45]

; __device__ __forceinline__ int lane_id_() { int l; asm volatile("v_mbcnt_lo_u32_b32 %0, -1, 0\n\tv_mbcnt_hi_u32_b32 %0, -1, %0" : "=v"(l)); return l; }
; __device__ __forceinline__ unsigned xb_add(unsigned* p, unsigned v) { return __hip_atomic_fetch_add(p, v, __ATOMIC_RELAXED, __HIP_MEMORY_SCOPE_AGENT); }
; __device__ __forceinline__ void xcd_barrier(const XcdBarrier& b, int wave_s) {
;     asm volatile("s_waitcnt vmcnt(0)" ::: "memory");
;     __syncthreads();
;     if (wave_s == 0 && lane_id_() == 0) {
;         unsigned* bar = b.bar;
;         __builtin_amdgcn_s_waitcnt(0);
;         unsigned nloc = b.st[0], nx = b.st[1];
;         if (nloc == 0u) { xcd_barrier_complete(bar, b.x, nloc, nx); b.st[0] = nloc; b.st[1] = nx; }
;         const unsigned old = xb_add(&bar[XB_XSUB(b.x)], 1u);
;         const unsigned gen = old / nloc;
;         if (old + 1u == (gen + 1u) * nloc) {
;             __builtin_amdgcn_fence(__ATOMIC_RELEASE, "agent");
;             asm volatile("s_waitcnt vmcnt(0)" ::: "memory");
;             const unsigned og = xb_add(&bar[XB_TOP], 1u);
.LBB0_682:
	s_waitcnt vmcnt(0)
	s_and_b64 vcc, exec, s[2:3]
	s_waitcnt vmcnt(0)
	s_barrier
	s_cbranch_vccnz .LBB0_736
	v_mbcnt_lo_u32_b32 v0, -1, 0
	v_mbcnt_hi_u32_b32 v0, -1, v0
	s_nop 0
	v_cmp_eq_u32_e32 vcc, 0, v0
	s_and_saveexec_b64 s[6:7], vcc
	s_cbranch_execz .LBB0_735
	s_cmp_eq_u32 s101, 1
	s_cbranch_scc0 .Lglob_S4
	s_and_b32 s98, s33, 7
	s_lshl_b32 s99, s98, 2
	s_addk_i32 s99, 0x4800
	v_mov_b32_e32 v3, s99
	s_lshl_b32 s98, s98, 8
	s_addk_i32 s98, 0x4000
	v_mov_b32_e32 v0, s98
	v_mov_b32_e32 v1, 1
	global_atomic_add v2, v0, v1, s[44:45] sc0
	s_waitcnt vmcnt(0)
	v_readfirstlane_b32 s98, v2
	s_nop 3
	s_add_u32 s99, s98, 1
	s_and_b32 s99, s99, 31
	s_lshr_b32 s98, s98, 5
	s_cmp_eq_u32 s99, 0
	s_cbranch_scc0 .Llw_S4
	global_atomic_add v3, v1, s[44:45]
	s_branch .Lla_S4

; __device__ __forceinline__ unsigned xb_ld(unsigned* p)              { return __hip_atomic_load(p, __ATOMIC_RELAXED, __HIP_MEMORY_SCOPE_AGENT); }
; __device__ __forceinline__ unsigned xb_add(unsigned* p, unsigned v) { return __hip_atomic_fetch_add(p, v, __ATOMIC_RELAXED, __HIP_MEMORY_SCOPE_AGENT); }
; #define XB_SPIN(cond, bar) do { unsigned _sp = 0; while (cond) { __builtin_amdgcn_s_sleep(1); \
;     if ((++_sp & 255u) == 0u) { if (xb_ld(&(bar)[XB_TMO])) break; if (_sp > XB_SPIN_CAP) { atomicAdd(&(bar)[XB_TMO], 1u); break; } } } } while (0)
; __device__ __forceinline__ void xcd_barrier(const XcdBarrier& b, int wave_s) {
;     ...
;             else XB_SPIN(xb_ld(&bar[XB_TOPGEN]) == tg, bar);
;             __builtin_amdgcn_fence(__ATOMIC_ACQUIRE, "agent");
;             xb_add(&bar[XB_XGEN(b.x)], 1u);
;             asm volatile("s_waitcnt vmcnt(0)" ::: "memory");
;         } else {
;             XB_SPIN(xb_ld(&bar[XB_XGEN(b.x)]) == gen, bar);
;             __builtin_amdgcn_fence(__ATOMIC_ACQUIRE, "agent");
;             asm volatile("s_waitcnt vmcnt(0)" ::: "memory");
;         }
.Lls_S4:
	global_load_dword v2, v3, s[44:45] sc1
	s_waitcnt vmcnt(0)
	v_readfirstlane_b32 s100, v2
	s_nop 3
	s_cmp_lg_u32 s100, s98
	s_cbranch_scc1 .Lla_S4
	s_sleep 1
	s_add_u32 s99, s99, 1
	s_cmp_lt_u32 s99, 0x4000
	s_cbranch_scc1 .Lls_S4

; __device__ __forceinline__ int lane_id_() { int l; asm volatile("v_mbcnt_lo_u32_b32 %0, -1, 0\n\tv_mbcnt_hi_u32_b32 %0, -1, %0" : "=v"(l)); return l; }
; __device__ __forceinline__ unsigned xb_add(unsigned* p, unsigned v) { return __hip_atomic_fetch_add(p, v, __ATOMIC_RELAXED, __HIP_MEMORY_SCOPE_AGENT); }
; __device__ __forceinline__ void xcd_barrier(const XcdBarrier& b, int wave_s) {
;     asm volatile("s_waitcnt vmcnt(0)" ::: "memory");
;     __syncthreads();
;     if (wave_s == 0 && lane_id_() == 0) {
;         unsigned* bar = b.bar;
;         __builtin_amdgcn_s_waitcnt(0);
;         unsigned nloc = b.st[0], nx = b.st[1];
;         if (nloc == 0u) { xcd_barrier_complete(bar, b.x, nloc, nx); b.st[0] = nloc; b.st[1] = nx; }
;         const unsigned old = xb_add(&bar[XB_XSUB(b.x)], 1u);
;         const unsigned gen = old / nloc;
;         if (old + 1u == (gen + 1u) * nloc) {
;             __builtin_amdgcn_fence(__ATOMIC_RELEASE, "agent");
;             asm volatile("s_waitcnt vmcnt(0)" ::: "memory");
;             const unsigned og = xb_add(&bar[XB_TOP], 1u);
.LBB0_749:
	s_waitcnt vmcnt(0)
	s_and_b64 vcc, exec, s[2:3]
	s_barrier
	s_cbranch_vccnz .LBB0_803
	v_mbcnt_lo_u32_b32 v0, -1, 0
	v_mbcnt_hi_u32_b32 v0, -1, v0
	s_nop 0
	v_cmp_eq_u32_e32 vcc, 0, v0
	s_and_saveexec_b64 s[6:7], vcc
	s_cbranch_execz .LBB0_802
	s_cmp_eq_u32 s101, 1
	s_cbranch_scc0 .Lglob_S5
	s_and_b32 s98, s33, 7
	s_lshl_b32 s99, s98, 2
	s_addk_i32 s99, 0x4800
	v_mov_b32_e32 v3, s99
	s_lshl_b32 s98, s98, 8
	s_addk_i32 s98, 0x4000
	v_mov_b32_e32 v0, s98
	v_mov_b32_e32 v1, 1
	global_atomic_add v2, v0, v1, s[44:45] sc0
	s_waitcnt vmcnt(0)
	v_readfirstlane_b32 s98, v2
	s_nop 3
	s_add_u32 s99, s98, 1
	s_and_b32 s99, s99, 31
	s_lshr_b32 s98, s98, 5
	s_cmp_eq_u32 s99, 0
	s_cbranch_scc0 .Llw_S5
	global_atomic_add v3, v1, s[44:45]
	s_branch .Lla_S5

; __device__ __forceinline__ int lane_id_() { int l; asm volatile("v_mbcnt_lo_u32_b32 %0, -1, 0\n\tv_mbcnt_hi_u32_b32 %0, -1, %0" : "=v"(l)); return l; }
; __device__ __forceinline__ unsigned xb_ld(unsigned* p)              { return __hip_atomic_load(p, __ATOMIC_RELAXED, __HIP_MEMORY_SCOPE_AGENT); }
; __device__ __forceinline__ void xcd_barrier_complete(unsigned* bar, unsigned x, unsigned& nloc, unsigned& nx) {
;     const unsigned G = gridDim.x * gridDim.y * gridDim.z;
;     unsigned sum, cnt, mine, sp = 0u;
;     for (;;) {
;         sum = 0u; cnt = 0u; mine = 0u;
; #pragma unroll
;         for (unsigned j = 0; j < 16; ++j) { const unsigned c = xb_ld(&bar[XB_XCNT(j)]); sum += c; cnt += (c > 0u) ? 1u : 0u; mine = (j == x) ? c : mine; }
;         if (sum == G) break;
;         __builtin_amdgcn_s_sleep(1);
;         if ((++sp & 255u) == 0u) { if (xb_ld(&bar[XB_TMO])) break; if (sp > XB_SPIN_CAP) { atomicAdd(&bar[XB_TMO], 1u); break; } }
;     }
;     nloc = mine > 0u ? mine : 1u; nx = cnt > 0u ? cnt : 1u;
; }
; __device__ __forceinline__ void xcd_barrier(const XcdBarrier& b, int wave_s) {
;     asm volatile("s_waitcnt vmcnt(0)" ::: "memory");
;     __syncthreads();
;     if (wave_s == 0 && lane_id_() == 0) {
;         unsigned* bar = b.bar;
;         __builtin_amdgcn_s_waitcnt(0);
;         unsigned nloc = b.st[0], nx = b.st[1];
;         if (nloc == 0u) { xcd_barrier_complete(bar, b.x, nloc, nx); b.st[0] = nloc; b.st[1] = nx; }
.Lglob_S6:
	s_add_i32 s8, 0, 0x21000
	v_mov_b32_e32 v0, s8
	s_waitcnt vmcnt(0) expcnt(0) lgkmcnt(0)
	ds_read_b32 v2, v0
	s_add_i32 s8, 0, 0x21004
	v_mov_b32_e32 v0, s8
	ds_read_b32 v0, v0
	s_waitcnt lgkmcnt(1)
	v_cmp_ne_u32_e32 vcc, 0, v2
	s_cbranch_vccnz .LBB0_864
	s_load_dword s8, s[0:1], 0xf8
	s_mov_b32 s25, 1
	v_mov_b32_e32 v16, 0
	s_waitcnt lgkmcnt(0)
	s_mul_i32 s24, s47, s8
	s_add_u32 s8, s44, 0x1000
	s_addc_u32 s9, s45, 0
	s_add_u32 s10, s44, 0x1100
	s_addc_u32 s11, s45, 0
	s_add_u32 s12, s44, 0x1200
	s_addc_u32 s13, s45, 0
	s_add_u32 s16, s44, 0x1300
	s_mul_i32 s24, s24, s46
	s_addc_u32 s17, s45, 0
	s_branch .LBB0_852

; __device__ __forceinline__ int lane_id_() { int l; asm volatile("v_mbcnt_lo_u32_b32 %0, -1, 0\n\tv_mbcnt_hi_u32_b32 %0, -1, %0" : "=v"(l)); return l; }
; __device__ __forceinline__ unsigned xb_add(unsigned* p, unsigned v) { return __hip_atomic_fetch_add(p, v, __ATOMIC_RELAXED, __HIP_MEMORY_SCOPE_AGENT); }
; __device__ __forceinline__ void xcd_barrier(const XcdBarrier& b, int wave_s) {
;     asm volatile("s_waitcnt vmcnt(0)" ::: "memory");
;     __syncthreads();
;     if (wave_s == 0 && lane_id_() == 0) {
;         unsigned* bar = b.bar;
;         __builtin_amdgcn_s_waitcnt(0);
;         unsigned nloc = b.st[0], nx = b.st[1];
;         if (nloc == 0u) { xcd_barrier_complete(bar, b.x, nloc, nx); b.st[0] = nloc; b.st[1] = nx; }
;         const unsigned old = xb_add(&bar[XB_XSUB(b.x)], 1u);
;         const unsigned gen = old / nloc;
;         if (old + 1u == (gen + 1u) * nloc) {
;             __builtin_amdgcn_fence(__ATOMIC_RELEASE, "agent");
;             asm volatile("s_waitcnt vmcnt(0)" ::: "memory");
;             const unsigned og = xb_add(&bar[XB_TOP], 1u);
.LBB0_1111:
	s_waitcnt vmcnt(0)
	s_and_b64 vcc, exec, s[2:3]
	s_waitcnt vmcnt(0)
	s_barrier
	s_cbranch_vccnz .LBB0_1165
	v_mbcnt_lo_u32_b32 v0, -1, 0
	v_mbcnt_hi_u32_b32 v0, -1, v0
	s_nop 0
	v_cmp_eq_u32_e32 vcc, 0, v0
	s_and_saveexec_b64 s[8:9], vcc
	s_cbranch_execz .LBB0_1164
	s_cmp_eq_u32 s101, 1
	s_cbranch_scc0 .Lglob_S7
	s_and_b32 s98, s33, 7
	s_lshl_b32 s99, s98, 2
	s_addk_i32 s99, 0x4800
	v_mov_b32_e32 v3, s99
	s_lshl_b32 s98, s98, 8
	s_addk_i32 s98, 0x4000
	v_mov_b32_e32 v0, s98
	v_mov_b32_e32 v1, 1
	global_atomic_add v2, v0, v1, s[44:45] sc0
	s_waitcnt vmcnt(0)
	v_readfirstlane_b32 s98, v2
	s_nop 3
	s_add_u32 s99, s98, 1
	s_and_b32 s99, s99, 31
	s_lshr_b32 s98, s98, 5
	s_cmp_eq_u32 s99, 0
	s_cbranch_scc0 .Llw_S7
	buffer_wbl2 sc1
	s_waitcnt vmcnt(0)
	global_atomic_add v3, v1, s[44:45]

; __device__ __forceinline__ int lane_id_() { int l; asm volatile("v_mbcnt_lo_u32_b32 %0, -1, 0\n\tv_mbcnt_hi_u32_b32 %0, -1, %0" : "=v"(l)); return l; }
; __device__ __forceinline__ unsigned xb_ld(unsigned* p)              { return __hip_atomic_load(p, __ATOMIC_RELAXED, __HIP_MEMORY_SCOPE_AGENT); }
; __device__ __forceinline__ void xcd_barrier_complete(unsigned* bar, unsigned x, unsigned& nloc, unsigned& nx) {
;     const unsigned G = gridDim.x * gridDim.y * gridDim.z;
;     unsigned sum, cnt, mine, sp = 0u;
;     for (;;) {
;         sum = 0u; cnt = 0u; mine = 0u;
; #pragma unroll
;         for (unsigned j = 0; j < 16; ++j) { const unsigned c = xb_ld(&bar[XB_XCNT(j)]); sum += c; cnt += (c > 0u) ? 1u : 0u; mine = (j == x) ? c : mine; }
;         if (sum == G) break;
;         __builtin_amdgcn_s_sleep(1);
;         if ((++sp & 255u) == 0u) { if (xb_ld(&bar[XB_TMO])) break; if (sp > XB_SPIN_CAP) { atomicAdd(&bar[XB_TMO], 1u); break; } }
;     }
;     nloc = mine > 0u ? mine : 1u; nx = cnt > 0u ? cnt : 1u;
; }
; __device__ __forceinline__ void xcd_barrier(const XcdBarrier& b, int wave_s) {
;     asm volatile("s_waitcnt vmcnt(0)" ::: "memory");
;     __syncthreads();
;     if (wave_s == 0 && lane_id_() == 0) {
;         unsigned* bar = b.bar;
;         __builtin_amdgcn_s_waitcnt(0);
;         unsigned nloc = b.st[0], nx = b.st[1];
;         if (nloc == 0u) { xcd_barrier_complete(bar, b.x, nloc, nx); b.st[0] = nloc; b.st[1] = nx; }
.Lglob_S7:
	s_add_i32 s6, 0, 0x21000
	v_mov_b32_e32 v0, s6
	s_waitcnt vmcnt(0) expcnt(0) lgkmcnt(0)
	ds_read_b32 v2, v0
	s_add_i32 s6, 0, 0x21004
	v_mov_b32_e32 v0, s6
	ds_read_b32 v0, v0
	s_waitcnt lgkmcnt(1)
	v_cmp_ne_u32_e32 vcc, 0, v2
	s_cbranch_vccnz .LBB0_1128
	s_add_u32 s10, s44, 0x1000
	s_load_dword s6, s[0:1], 0xf8
	s_addc_u32 s11, s45, 0
	s_add_u32 s12, s44, 0x1100
	s_addc_u32 s13, s45, 0
	s_add_u32 s18, s44, 0x1200
	s_addc_u32 s19, s45, 0
	s_waitcnt lgkmcnt(0)
	s_mul_i32 s6, s47, s6
	s_add_u32 s20, s44, 0x1300
	s_mul_i32 s6, s6, s46
	s_addc_u32 s21, s45, 0
	s_mov_b32 s7, 1
	v_mov_b32_e32 v16, 0
	s_branch .LBB0_1116

; __device__ __forceinline__ int lane_id_() { int l; asm volatile("v_mbcnt_lo_u32_b32 %0, -1, 0\n\tv_mbcnt_hi_u32_b32 %0, -1, %0" : "=v"(l)); return l; }
; __device__ __forceinline__ unsigned xb_add(unsigned* p, unsigned v) { return __hip_atomic_fetch_add(p, v, __ATOMIC_RELAXED, __HIP_MEMORY_SCOPE_AGENT); }
; __device__ __forceinline__ void xcd_barrier(const XcdBarrier& b, int wave_s) {
;     asm volatile("s_waitcnt vmcnt(0)" ::: "memory");
;     __syncthreads();
;     if (wave_s == 0 && lane_id_() == 0) {
;         unsigned* bar = b.bar;
;         __builtin_amdgcn_s_waitcnt(0);
;         unsigned nloc = b.st[0], nx = b.st[1];
;         if (nloc == 0u) { xcd_barrier_complete(bar, b.x, nloc, nx); b.st[0] = nloc; b.st[1] = nx; }
;         const unsigned old = xb_add(&bar[XB_XSUB(b.x)], 1u);
;         const unsigned gen = old / nloc;
;         if (old + 1u == (gen + 1u) * nloc) {
;             __builtin_amdgcn_fence(__ATOMIC_RELEASE, "agent");
;             asm volatile("s_waitcnt vmcnt(0)" ::: "memory");
;             const unsigned og = xb_add(&bar[XB_TOP], 1u);
.LBB0_1213:
	s_waitcnt vmcnt(0)
	s_and_b64 vcc, exec, s[2:3]
	s_waitcnt lgkmcnt(0)
	s_barrier
	s_cbranch_vccnz .LBB0_1267
	v_mbcnt_lo_u32_b32 v0, -1, 0
	v_mbcnt_hi_u32_b32 v0, -1, v0
	s_nop 0
	v_cmp_eq_u32_e32 vcc, 0, v0
	s_and_saveexec_b64 s[8:9], vcc
	s_cbranch_execz .LBB0_1266
	s_cmp_eq_u32 s101, 1
	s_cbranch_scc0 .Lglob_S8
	s_and_b32 s98, s33, 7
	s_lshl_b32 s99, s98, 2
	s_addk_i32 s99, 0x4800
	v_mov_b32_e32 v3, s99
	s_lshl_b32 s98, s98, 8
	s_addk_i32 s98, 0x4000
	v_mov_b32_e32 v0, s98
	v_mov_b32_e32 v1, 1
	global_atomic_add v2, v0, v1, s[44:45] sc0
	s_waitcnt vmcnt(0)
	v_readfirstlane_b32 s98, v2
	s_nop 3
	s_add_u32 s99, s98, 1
	s_and_b32 s99, s99, 31
	s_lshr_b32 s98, s98, 5
	s_cmp_eq_u32 s99, 0
	s_cbranch_scc0 .Llw_S8
	global_atomic_add v3, v1, s[44:45]
	s_branch .Lla_S8

; __device__ __forceinline__ int lane_id_() { int l; asm volatile("v_mbcnt_lo_u32_b32 %0, -1, 0\n\tv_mbcnt_hi_u32_b32 %0, -1, %0" : "=v"(l)); return l; }
; __device__ __forceinline__ unsigned xb_add(unsigned* p, unsigned v) { return __hip_atomic_fetch_add(p, v, __ATOMIC_RELAXED, __HIP_MEMORY_SCOPE_AGENT); }
; __device__ __forceinline__ void xcd_barrier(const XcdBarrier& b, int wave_s) {
;     asm volatile("s_waitcnt vmcnt(0)" ::: "memory");
;     __syncthreads();
;     if (wave_s == 0 && lane_id_() == 0) {
;         unsigned* bar = b.bar;
;         __builtin_amdgcn_s_waitcnt(0);
;         unsigned nloc = b.st[0], nx = b.st[1];
;         if (nloc == 0u) { xcd_barrier_complete(bar, b.x, nloc, nx); b.st[0] = nloc; b.st[1] = nx; }
;         const unsigned old = xb_add(&bar[XB_XSUB(b.x)], 1u);
;         const unsigned gen = old / nloc;
;         if (old + 1u == (gen + 1u) * nloc) {
;             __builtin_amdgcn_fence(__ATOMIC_RELEASE, "agent");
;             asm volatile("s_waitcnt vmcnt(0)" ::: "memory");
;             const unsigned og = xb_add(&bar[XB_TOP], 1u);
.LBB0_1589:
	s_waitcnt vmcnt(0)
	s_and_b64 vcc, exec, s[2:3]
	s_waitcnt vmcnt(0)
	s_barrier
	s_cbranch_vccnz .LBB0_1643
	v_mbcnt_lo_u32_b32 v0, -1, 0
	v_mbcnt_hi_u32_b32 v0, -1, v0
	s_nop 0
	v_cmp_eq_u32_e32 vcc, 0, v0
	s_and_saveexec_b64 s[8:9], vcc
	s_cbranch_execz .LBB0_1642
	s_cmp_eq_u32 s101, 1
	s_cbranch_scc0 .Lglob_S9
	s_and_b32 s98, s33, 7
	s_lshl_b32 s99, s98, 2
	s_addk_i32 s99, 0x4800
	v_mov_b32_e32 v3, s99
	s_lshl_b32 s98, s98, 8
	s_addk_i32 s98, 0x4000
	v_mov_b32_e32 v0, s98
	v_mov_b32_e32 v1, 1
	global_atomic_add v2, v0, v1, s[44:45] sc0
	s_waitcnt vmcnt(0)
	v_readfirstlane_b32 s98, v2
	s_nop 3
	s_add_u32 s99, s98, 1
	s_and_b32 s99, s99, 31
	s_lshr_b32 s98, s98, 5
	s_cmp_eq_u32 s99, 0
	s_cbranch_scc0 .Llw_S9
	global_atomic_add v3, v1, s[44:45]
	s_branch .Lla_S9

; __device__ __forceinline__ int lane_id_() { int l; asm volatile("v_mbcnt_lo_u32_b32 %0, -1, 0\n\tv_mbcnt_hi_u32_b32 %0, -1, %0" : "=v"(l)); return l; }
; __device__ __forceinline__ unsigned xb_add(unsigned* p, unsigned v) { return __hip_atomic_fetch_add(p, v, __ATOMIC_RELAXED, __HIP_MEMORY_SCOPE_AGENT); }
; __device__ __forceinline__ void xcd_barrier(const XcdBarrier& b, int wave_s) {
;     asm volatile("s_waitcnt vmcnt(0)" ::: "memory");
;     __syncthreads();
;     if (wave_s == 0 && lane_id_() == 0) {
;         unsigned* bar = b.bar;
;         __builtin_amdgcn_s_waitcnt(0);
;         unsigned nloc = b.st[0], nx = b.st[1];
;         if (nloc == 0u) { xcd_barrier_complete(bar, b.x, nloc, nx); b.st[0] = nloc; b.st[1] = nx; }
;         const unsigned old = xb_add(&bar[XB_XSUB(b.x)], 1u);
;         const unsigned gen = old / nloc;
;         if (old + 1u == (gen + 1u) * nloc) {
;             __builtin_amdgcn_fence(__ATOMIC_RELEASE, "agent");
;             asm volatile("s_waitcnt vmcnt(0)" ::: "memory");
;             const unsigned og = xb_add(&bar[XB_TOP], 1u);
.LBB0_1691:
	s_waitcnt vmcnt(0)
	s_and_b64 vcc, exec, s[2:3]
	s_waitcnt lgkmcnt(0)
	s_barrier
	s_cbranch_vccnz .LBB0_1745
	v_mbcnt_lo_u32_b32 v0, -1, 0
	v_mbcnt_hi_u32_b32 v0, -1, v0
	s_nop 0
	v_cmp_eq_u32_e32 vcc, 0, v0
	s_and_saveexec_b64 s[8:9], vcc
	s_cbranch_execz .LBB0_1744
	s_cmp_eq_u32 s101, 1
	s_cbranch_scc0 .Lglob_S10
	s_and_b32 s98, s33, 7
	s_lshl_b32 s99, s98, 2
	s_addk_i32 s99, 0x4800
	v_mov_b32_e32 v3, s99
	s_lshl_b32 s98, s98, 8
	s_addk_i32 s98, 0x4000
	v_mov_b32_e32 v0, s98
	v_mov_b32_e32 v1, 1
	global_atomic_add v2, v0, v1, s[44:45] sc0
	s_waitcnt vmcnt(0)
	v_readfirstlane_b32 s98, v2
	s_nop 3
	s_add_u32 s99, s98, 1
	s_and_b32 s99, s99, 31
	s_lshr_b32 s98, s98, 5
	s_cmp_eq_u32 s99, 0
	s_cbranch_scc0 .Llw_S10
	buffer_wbl2 sc1
	s_waitcnt vmcnt(0)
	global_atomic_add v3, v1, s[44:45]

; __device__ __forceinline__ int lane_id_() { int l; asm volatile("v_mbcnt_lo_u32_b32 %0, -1, 0\n\tv_mbcnt_hi_u32_b32 %0, -1, %0" : "=v"(l)); return l; }
; __device__ __forceinline__ unsigned xb_add(unsigned* p, unsigned v) { return __hip_atomic_fetch_add(p, v, __ATOMIC_RELAXED, __HIP_MEMORY_SCOPE_AGENT); }
; __device__ __forceinline__ void xcd_barrier(const XcdBarrier& b, int wave_s) {
;     asm volatile("s_waitcnt vmcnt(0)" ::: "memory");
;     __syncthreads();
;     if (wave_s == 0 && lane_id_() == 0) {
;         unsigned* bar = b.bar;
;         __builtin_amdgcn_s_waitcnt(0);
;         unsigned nloc = b.st[0], nx = b.st[1];
;         if (nloc == 0u) { xcd_barrier_complete(bar, b.x, nloc, nx); b.st[0] = nloc; b.st[1] = nx; }
;         const unsigned old = xb_add(&bar[XB_XSUB(b.x)], 1u);
;         const unsigned gen = old / nloc;
;         if (old + 1u == (gen + 1u) * nloc) {
;             __builtin_amdgcn_fence(__ATOMIC_RELEASE, "agent");
;             asm volatile("s_waitcnt vmcnt(0)" ::: "memory");
;             const unsigned og = xb_add(&bar[XB_TOP], 1u);
.LBB0_2397:
	s_waitcnt vmcnt(0)
	s_and_b64 vcc, exec, s[2:3]
	s_waitcnt vmcnt(0)
	s_barrier
	s_cbranch_vccnz .LBB0_2451
	v_mbcnt_lo_u32_b32 v0, -1, 0
	v_mbcnt_hi_u32_b32 v0, -1, v0
	s_nop 0
	v_cmp_eq_u32_e32 vcc, 0, v0
	s_and_saveexec_b64 s[2:3], vcc
	s_cbranch_execz .LBB0_2450
	s_cmp_eq_u32 s101, 1
	s_cbranch_scc0 .Lglob_S14
	s_and_b32 s98, s33, 7
	s_lshl_b32 s99, s98, 2
	s_addk_i32 s99, 0x4800
	v_mov_b32_e32 v3, s99
	s_lshl_b32 s98, s98, 8
	s_addk_i32 s98, 0x4000
	v_mov_b32_e32 v0, s98
	v_mov_b32_e32 v1, 1
	global_atomic_add v2, v0, v1, s[44:45] sc0
	s_waitcnt vmcnt(0)
	v_readfirstlane_b32 s98, v2
	s_nop 3
	s_add_u32 s99, s98, 1
	s_and_b32 s99, s99, 31
	s_lshr_b32 s98, s98, 5
	s_cmp_eq_u32 s99, 0
	s_cbranch_scc0 .Llw_S14
	global_atomic_add v3, v1, s[44:45]
	s_branch .Lla_S14
